# speedup vs baseline: 1.0122x; 1.0078x over previous
; DI void ssm_prompt_unit(LAS unsigned char* lds, int unit, int tid, int l, const bf16_t* U, const bf16_t* mats_l, const float* lam16_l, bf16_t* Z, float* outr_l, float* outi_l) {
;     const int b = unit >> 6, g = unit & 63, wave = tid >> 6, lane = tid & 63, l32 = lane & 31, h = lane >> 5;
;     const bf16_t* mats = mats_l + (size_t)g * SSMM_PER;
;     bf16x8 bfr[16];
;     {
;         const bf16_t* bp = mats + 65536 + (size_t)((wave & 3) * 32 + l32) * 256 + 8 * h;
; #pragma unroll
;         for (int ks = 0; ks < 16; ++ks) bfr[ks] = *(const bf16x8*)(bp + 16 * ks);
;     }
;     u32x4 uv[8];
; #pragma unroll
;     for (int i = 0; i < 8; ++i) { const int idx = tid + i * NTHREADS, t = idx >> 1, half = idx & 1; uv[i] = *(const u32x4*)(U + (size_t)(b * SEQ + t) * SW + g * 16 + 8 * half); }
;     __syncthreads();
; #pragma unroll
;     for (int i = 0; i < 8; ++i) { const int idx = tid + i * NTHREADS, t = idx >> 1, half = idx & 1; *(LAS u32x4*)(lds + (t >> 4) * UP_PITCH + ((t & 15) * 16 + 8 * half) * 2) = uv[i]; }
;     if (tid < 64) *(LAS unsigned*)(lds + SH_OFF + tid * 4) = 0u;
;     __syncthreads();
;     {
;         const int nt = wave & 3, mt0 = 2 * (wave >> 2);
;         f32x16 acc[2];
; #pragma unroll
;         for (int i = 0; i < 16; ++i) { acc[0][i] = 0.f; acc[1][i] = 0.f; }
; #pragma unroll
;         for (int ks = 0; ks < 16; ++ks) {
;             const bf16x8 bf = bfr[ks];
; #pragma unroll
;             for (int mi = 0; mi < 2; ++mi) { const bf16x8 af = *(const LAS bf16x8*)(lds + ((mt0 + mi) * 32 + l32) * UP_PITCH + (16 * ks + 8 * h) * 2); acc[mi] = MFMA32(af, bf, acc[mi]); }
;         }
; #pragma unroll
;         for (int mi = 0; mi < 2; ++mi)
; #pragma unroll
;             for (int i = 0; i < 16; ++i) *(LAS float*)(lds + SH_OFF + ((mt0 + mi) * 32 + crow(i, h) + 1) * UP_PITCH + (nt * 32 + l32) * 4) = acc[mi][i];
;     }
;     bf16x8 kfr[16];
;     {
;         const bf16_t* kp = mats + (size_t)(wave * 32 + l32) * 256 + 8 * h;
; #pragma unroll
;         for (int ks = 0; ks < 16; ++ks) kfr[ks] = *(const bf16x8*)(kp + 16 * ks);
;     }
;     ...
;                 const int tok = 16 * (mt * 32 + l32) + 2 * wave + (g4 >> 1), c0 = 8 * (g4 & 1) + 4 * h;
;                 u32x2 w; w.x = pk2(gelu_tanh(acc[mt][4 * g4]), gelu_tanh(acc[mt][4 * g4 + 1])); w.y = pk2(gelu_tanh(acc[mt][4 * g4 + 2]), gelu_tanh(acc[mt][4 * g4 + 3]));
.LBB0_396:
	s_or_b64 exec, exec, s[0:1]
	v_readlane_b32 s0, v254, 53
	v_readlane_b32 s1, v254, 54
	s_lshl_b64 s[42:43], s[0:1], 15
	v_readlane_b32 s0, v252, 52
	v_readlane_b32 s1, v252, 53
	s_mov_b32 s94, s0
	v_readlane_b32 s0, v252, 54
	v_readlane_b32 s1, v252, 55
	s_and_b64 vcc, exec, s[0:1]
	s_waitcnt lgkmcnt(0)
	s_barrier
	v_mbcnt_lo_u32_b32 v156, -1, 0
	v_mbcnt_hi_u32_b32 v156, -1, v156
	s_cbranch_vccz .LBB0_408
	v_readlane_b32 s0, v254, 53
	v_readlane_b32 s1, v254, 54
	v_lshl_add_u32 v157, s94, 6, v156
	v_lshlrev_b32_e32 v5, 4, v156
	s_lshl_b64 s[0:1], s[0:1], 24
	v_readlane_b32 s6, v252, 48
	v_and_b32_e32 v160, 16, v5
	v_add_u32_e32 v5, 0x200, v157
	s_add_u32 s56, s6, s0
	v_readlane_b32 s0, v252, 49
	v_ashrrev_i32_e32 v175, 1, v5
	v_add_u32_e32 v6, 0x400, v157
	s_movk_i32 s7, 0x210
	v_ashrrev_i32_e32 v5, 5, v5
	s_addc_u32 s57, s0, s1
	v_readlane_b32 s0, v255, 57
	v_add_u32_e32 v7, 0x600, v157
	v_mul_lo_u32 v14, v5, s7
	v_ashrrev_i32_e32 v5, 5, v6
	s_add_u32 s0, s0, s42
	v_readlane_b32 s1, v255, 58
	v_ashrrev_i32_e32 v176, 1, v6
	v_add_u32_e32 v8, 0x800, v157
	v_mul_lo_u32 v6, v5, s7
	v_ashrrev_i32_e32 v5, 5, v7
	s_addc_u32 s1, s1, s43
	v_readlane_b32 s6, v255, 59
	v_ashrrev_i32_e32 v177, 1, v7
	v_add_u32_e32 v9, 0xa00, v157
	v_mul_lo_u32 v7, v5, s7
	v_ashrrev_i32_e32 v5, 5, v8
	s_add_u32 s44, s6, s50
	v_readlane_b32 s6, v255, 60
	v_ashrrev_i32_e32 v178, 1, v8
	v_add_u32_e32 v10, 0xc00, v157
	v_mul_lo_u32 v8, v5, s7
	v_ashrrev_i32_e32 v5, 5, v9
	s_addc_u32 s45, s6, s51
	v_readlane_b32 s6, v255, 61
	v_ashrrev_i32_e32 v179, 1, v9
	v_add_u32_e32 v11, 0xe00, v157
	v_mul_lo_u32 v9, v5, s7
	v_ashrrev_i32_e32 v5, 5, v10
	s_add_u32 s46, s6, s50
	v_readlane_b32 s6, v255, 62
	v_ashrrev_i32_e32 v180, 1, v10
	v_mul_lo_u32 v10, v5, s7
	v_ashrrev_i32_e32 v5, 5, v11
	s_addc_u32 s47, s6, s51
	v_and_b32_e32 v1, 31, v156
	v_bfe_u32 v3, v156, 5, 1
	v_ashrrev_i32_e32 v174, 1, v157
	s_movk_i32 s6, 0x60
	v_ashrrev_i32_e32 v181, 1, v11
	v_mul_lo_u32 v11, v5, s7
	v_ashrrev_i32_e32 v5, 2, v157
	v_and_or_b32 v4, v174, s6, v1
	v_lshlrev_b32_e32 v2, 3, v3
	v_lshlrev_b32_e32 v16, 4, v3
	v_and_b32_e32 v5, 0xffffffc0, v5
	v_lshlrev_b32_e32 v3, 2, v3
	v_lshlrev_b32_e32 v0, 8, v4
	v_lshlrev_b32_e32 v21, 2, v4
	v_or_b32_e32 v4, v5, v3
	v_mul_lo_u32 v4, v4, s7
	v_readlane_b32 s14, v254, 22
	s_movk_i32 s6, 0xffe0
	v_lshlrev_b32_e32 v12, 4, v157
	v_or_b32_e32 v19, 32, v5
	v_add_u32_e32 v22, s14, v4
	v_bfi_b32 v4, s6, v174, v156
	v_and_b32_e32 v13, 0x1e0, v12
	v_and_b32_e32 v12, 16, v12
	v_add_u32_e32 v17, 0, v16
	v_or_b32_e32 v18, v5, v1
	v_or_b32_e32 v3, v19, v3
	v_ashrrev_i32_e32 v5, 31, v4
	v_add3_u32 v12, 0, v13, v12
	v_ashrrev_i32_e32 v13, 5, v157
	v_lshlrev_b32_e32 v15, 2, v157
	v_or_b32_e32 v20, v19, v1
	v_mul_lo_u32 v3, v3, s7
	v_lshlrev_b64 v[166:167], 9, v[4:5]
	v_lshlrev_b64 v[168:169], 8, v[4:5]
	v_mul_u32_u24_e32 v4, 0x210, v1
	v_mad_u32_u24 v182, v1, s7, v17
	v_add_u32_e32 v5, s14, v16
	v_lshlrev_b32_e32 v1, 9, v1
	v_and_b32_e32 v16, 0xffffffc0, v157
	v_mul_lo_u32 v13, v13, s7
	v_mul_lo_u32 v18, v18, s7
	v_mul_lo_u32 v20, v20, s7
	v_add_u32_e32 v3, s14, v3
	v_add3_u32 v1, 0, v16, v1
	v_lshlrev_b32_e32 v172, 1, v0
	v_add_u32_e32 v0, 0, v15
	v_lshl_add_u64 v[158:159], s[4:5], 0, v[160:161]
	v_cmp_gt_i32_e64 s[36:37], 64, v157
	v_cmp_gt_u32_e64 s[38:39], 64, v157
	v_cmp_gt_i32_e64 s[40:41], s17, v157
	v_add_u32_e32 v183, 0, v160
	v_lshl_add_u64 v[170:171], s[12:13], 0, v[160:161]
	v_lshlrev_b32_e32 v160, 1, v2
	v_add_u32_e32 v184, v12, v13
	v_add_u32_e32 v185, v12, v14
	v_add_u32_e32 v186, v12, v6
	v_add_u32_e32 v187, v12, v7
	v_add_u32_e32 v188, v12, v8
	v_add_u32_e32 v189, v12, v9
	v_add_u32_e32 v190, v12, v10
	v_add_u32_e32 v191, v12, v11
	v_add_u32_e32 v192, 0x10800, v0
	v_add_u32_e32 v193, v17, v18
	v_add_u32_e32 v194, v17, v20
	v_add_u32_e32 v195, v22, v21
	v_add_u32_e32 v196, v3, v21
	v_add_u32_e32 v197, v5, v4
	v_add_u32_e32 v198, v1, v2
	v_and_b32_e32 v199, 31, v156
	v_lshl_add_u32 v198, v199, 4, v198
	v_readlane_b32 s48, v254, 44
	v_readlane_b32 s49, v254, 45
	s_branch .LBB0_399

; #define LAS __attribute__((address_space(3)))
; #define MFMA32(a, b, c) __builtin_amdgcn_mfma_f32_32x32x16_bf16((a), (b), (c), 0, 0, 0)
; DI void ssm_prompt_unit(LAS unsigned char* lds, int unit, int tid, int l, const bf16_t* U, const bf16_t* mats_l, const float* lam16_l, bf16_t* Z, float* outr_l, float* outi_l) {
;     ...
;     {
;         bf16x8 cfr[8];
;         {
;             const bf16_t* cp = mats + 98304 + (size_t)(wave * 32 + l32) * 128 + 8 * h;
; #pragma unroll
;             for (int ks = 0; ks < 8; ++ks) cfr[ks] = *(const bf16x8*)(cp + 16 * ks);
;         }
;         f32x16 acc[4];
; #pragma unroll
;         for (int mt = 0; mt < 4; ++mt)
; #pragma unroll
;             for (int i = 0; i < 16; ++i) acc[mt][i] = 0.f;
; #pragma unroll
;         for (int ks = 0; ks < 16; ++ks) {
;             const bf16x8 af = kfr[ks];
; #pragma unroll
;             for (int mt = 0; mt < 4; ++mt) { const bf16x8 bf = *(const LAS bf16x8*)(lds + (mt * 32 + l32) * UP_PITCH + (16 * ks + 8 * h) * 2); acc[mt] = MFMA32(af, bf, acc[mt]); }
;         }
.LBB0_405:
	s_or_b64 exec, exec, s[54:55]
	v_lshl_add_u64 v[4:5], s[52:53], 0, v[168:169]
	s_lshl_b32 s14, s6, 4
	v_lshl_add_u64 v[4:5], v[4:5], 0, v[160:161]
	s_mov_b64 s[6:7], 0x30000
	v_lshl_add_u64 v[6:7], v[4:5], 0, s[6:7]
	v_add_co_u32_e32 v4, vcc, 0x30000, v4
	s_waitcnt lgkmcnt(0)
	s_nop 0
	v_addc_co_u32_e32 v5, vcc, 0, v5, vcc
	s_barrier
	global_load_dwordx4 v[152:155], v[4:5], off
	global_load_dwordx4 v[148:151], v[6:7], off offset:32
	global_load_dwordx4 v[144:147], v[6:7], off offset:64
	global_load_dwordx4 v[140:143], v[6:7], off offset:96
	global_load_dwordx4 v[136:139], v[6:7], off offset:128
	global_load_dwordx4 v[132:135], v[6:7], off offset:160
	global_load_dwordx4 v[128:131], v[6:7], off offset:192
	global_load_dwordx4 v[124:127], v[6:7], off offset:224
	ds_read_b128 v[4:7], v182
	ds_read_b128 v[162:165], v182 offset:32
	s_waitcnt vmcnt(23) lgkmcnt(1)
	v_mfma_f32_32x32x16_bf16 v[48:63], v[0:3], v[4:7], 0
	ds_read_b128 v[4:7], v182 offset:16896
	s_waitcnt vmcnt(22) lgkmcnt(1)
	v_mfma_f32_32x32x16_bf16 v[48:63], v[120:123], v[162:165], v[48:63]
	ds_read_b128 v[162:165], v182 offset:16928
	s_waitcnt lgkmcnt(1)
	v_mfma_f32_32x32x16_bf16 v[32:47], v[0:3], v[4:7], 0
	ds_read_b128 v[4:7], v182 offset:33792
	s_waitcnt lgkmcnt(1)
	v_mfma_f32_32x32x16_bf16 v[32:47], v[120:123], v[162:165], v[32:47]
	ds_read_b128 v[162:165], v182 offset:33824
	s_waitcnt lgkmcnt(1)
	v_mfma_f32_32x32x16_bf16 v[16:31], v[0:3], v[4:7], 0
	ds_read_b128 v[4:7], v182 offset:50688
	s_waitcnt lgkmcnt(1)
	v_mfma_f32_32x32x16_bf16 v[16:31], v[120:123], v[162:165], v[16:31]
	ds_read_b128 v[162:165], v182 offset:50720
	s_waitcnt lgkmcnt(1)
	v_mfma_f32_32x32x16_bf16 v[0:15], v[0:3], v[4:7], 0
	s_waitcnt lgkmcnt(0)
	v_mfma_f32_32x32x16_bf16 v[0:15], v[120:123], v[162:165], v[0:15]
	ds_read_b128 v[120:123], v182 offset:64
	s_waitcnt vmcnt(21) lgkmcnt(0)
	v_mfma_f32_32x32x16_bf16 v[48:63], v[116:119], v[120:123], v[48:63]
	ds_read_b128 v[120:123], v182 offset:16960
	s_waitcnt lgkmcnt(0)
	v_mfma_f32_32x32x16_bf16 v[32:47], v[116:119], v[120:123], v[32:47]
	ds_read_b128 v[120:123], v182 offset:33856
	s_waitcnt lgkmcnt(0)
	v_mfma_f32_32x32x16_bf16 v[16:31], v[116:119], v[120:123], v[16:31]
	ds_read_b128 v[120:123], v182 offset:50752
	s_waitcnt lgkmcnt(0)
	v_mfma_f32_32x32x16_bf16 v[0:15], v[116:119], v[120:123], v[0:15]
	ds_read_b128 v[116:119], v182 offset:96
	s_waitcnt vmcnt(20) lgkmcnt(0)
	v_mfma_f32_32x32x16_bf16 v[48:63], v[112:115], v[116:119], v[48:63]
	ds_read_b128 v[116:119], v182 offset:16992
	s_waitcnt lgkmcnt(0)
	v_mfma_f32_32x32x16_bf16 v[32:47], v[112:115], v[116:119], v[32:47]
	ds_read_b128 v[116:119], v182 offset:33888
	s_waitcnt lgkmcnt(0)
	v_mfma_f32_32x32x16_bf16 v[16:31], v[112:115], v[116:119], v[16:31]
	ds_read_b128 v[116:119], v182 offset:50784
	s_waitcnt lgkmcnt(0)
	v_mfma_f32_32x32x16_bf16 v[0:15], v[112:115], v[116:119], v[0:15]
	ds_read_b128 v[112:115], v182 offset:128
	s_waitcnt vmcnt(19) lgkmcnt(0)
	v_mfma_f32_32x32x16_bf16 v[48:63], v[108:111], v[112:115], v[48:63]
	ds_read_b128 v[112:115], v182 offset:17024
	s_waitcnt lgkmcnt(0)
	v_mfma_f32_32x32x16_bf16 v[32:47], v[108:111], v[112:115], v[32:47]
	ds_read_b128 v[112:115], v182 offset:33920
	s_waitcnt lgkmcnt(0)
	v_mfma_f32_32x32x16_bf16 v[16:31], v[108:111], v[112:115], v[16:31]
	ds_read_b128 v[112:115], v182 offset:50816
	s_waitcnt lgkmcnt(0)
	v_mfma_f32_32x32x16_bf16 v[0:15], v[108:111], v[112:115], v[0:15]
	ds_read_b128 v[108:111], v182 offset:160
	s_waitcnt vmcnt(18) lgkmcnt(0)
	v_mfma_f32_32x32x16_bf16 v[48:63], v[104:107], v[108:111], v[48:63]
	ds_read_b128 v[108:111], v182 offset:17056
	s_waitcnt lgkmcnt(0)
	v_mfma_f32_32x32x16_bf16 v[32:47], v[104:107], v[108:111], v[32:47]
	ds_read_b128 v[108:111], v182 offset:33952
	s_waitcnt lgkmcnt(0)
	v_mfma_f32_32x32x16_bf16 v[16:31], v[104:107], v[108:111], v[16:31]
	ds_read_b128 v[108:111], v182 offset:50848
	s_waitcnt lgkmcnt(0)
	v_mfma_f32_32x32x16_bf16 v[0:15], v[104:107], v[108:111], v[0:15]
	ds_read_b128 v[104:107], v182 offset:192
	s_waitcnt vmcnt(17) lgkmcnt(0)
	v_mfma_f32_32x32x16_bf16 v[48:63], v[100:103], v[104:107], v[48:63]
	ds_read_b128 v[104:107], v182 offset:17088
	s_waitcnt lgkmcnt(0)
	v_mfma_f32_32x32x16_bf16 v[32:47], v[100:103], v[104:107], v[32:47]
	ds_read_b128 v[104:107], v182 offset:33984
	s_waitcnt lgkmcnt(0)
	v_mfma_f32_32x32x16_bf16 v[16:31], v[100:103], v[104:107], v[16:31]
	ds_read_b128 v[104:107], v182 offset:50880
	s_waitcnt lgkmcnt(0)
	v_mfma_f32_32x32x16_bf16 v[0:15], v[100:103], v[104:107], v[0:15]
	ds_read_b128 v[100:103], v182 offset:224
	s_waitcnt vmcnt(16) lgkmcnt(0)
	v_mfma_f32_32x32x16_bf16 v[48:63], v[96:99], v[100:103], v[48:63]
	ds_read_b128 v[100:103], v182 offset:17120
	s_waitcnt lgkmcnt(0)
	v_mfma_f32_32x32x16_bf16 v[32:47], v[96:99], v[100:103], v[32:47]
	ds_read_b128 v[100:103], v182 offset:34016
	s_waitcnt lgkmcnt(0)
	v_mfma_f32_32x32x16_bf16 v[16:31], v[96:99], v[100:103], v[16:31]
	ds_read_b128 v[100:103], v182 offset:50912
	s_waitcnt lgkmcnt(0)
	v_mfma_f32_32x32x16_bf16 v[0:15], v[96:99], v[100:103], v[0:15]
	ds_read_b128 v[96:99], v182 offset:256
	s_waitcnt vmcnt(15) lgkmcnt(0)
	v_mfma_f32_32x32x16_bf16 v[48:63], v[92:95], v[96:99], v[48:63]
	ds_read_b128 v[96:99], v182 offset:17152
	s_waitcnt lgkmcnt(0)
	v_mfma_f32_32x32x16_bf16 v[32:47], v[92:95], v[96:99], v[32:47]
	ds_read_b128 v[96:99], v182 offset:34048
	s_waitcnt lgkmcnt(0)
	v_mfma_f32_32x32x16_bf16 v[16:31], v[92:95], v[96:99], v[16:31]
	ds_read_b128 v[96:99], v182 offset:50944
	s_waitcnt lgkmcnt(0)
	v_mfma_f32_32x32x16_bf16 v[0:15], v[92:95], v[96:99], v[0:15]
	ds_read_b128 v[92:95], v182 offset:288
	s_waitcnt vmcnt(14) lgkmcnt(0)
; #define LAS __attribute__((address_space(3)))
; #define MFMA32(a, b, c) __builtin_amdgcn_mfma_f32_32x32x16_bf16((a), (b), (c), 0, 0, 0)
; DI void ssm_prompt_unit(LAS unsigned char* lds, int unit, int tid, int l, const bf16_t* U, const bf16_t* mats_l, const float* lam16_l, bf16_t* Z, float* outr_l, float* outi_l) {
;     ...
;         for (int ks = 0; ks < 16; ++ks) {
;             const bf16x8 af = kfr[ks];
; #pragma unroll
;             for (int mt = 0; mt < 4; ++mt) { const bf16x8 bf = *(const LAS bf16x8*)(lds + (mt * 32 + l32) * UP_PITCH + (16 * ks + 8 * h) * 2); acc[mt] = MFMA32(af, bf, acc[mt]); }
;         }
; #pragma unroll
;         for (int ks = 0; ks < 8; ++ks) {
;             const bf16x8 af = cfr[ks];
; #pragma unroll
;             for (int mt = 0; mt < 4; ++mt) { const bf16x8 bf = *(const LAS bf16x8*)(lds + SH_OFF + (mt * 32 + l32) * UP_PITCH + (16 * ks + 8 * h) * 2); acc[mt] = MFMA32(af, bf, acc[mt]); }
;         }
	v_mfma_f32_32x32x16_bf16 v[48:63], v[88:91], v[92:95], v[48:63]
	ds_read_b128 v[92:95], v182 offset:17184
	s_waitcnt lgkmcnt(0)
	v_mfma_f32_32x32x16_bf16 v[32:47], v[88:91], v[92:95], v[32:47]
	ds_read_b128 v[92:95], v182 offset:34080
	s_waitcnt lgkmcnt(0)
	v_mfma_f32_32x32x16_bf16 v[16:31], v[88:91], v[92:95], v[16:31]
	ds_read_b128 v[92:95], v182 offset:50976
	s_waitcnt lgkmcnt(0)
	v_mfma_f32_32x32x16_bf16 v[0:15], v[88:91], v[92:95], v[0:15]
	ds_read_b128 v[88:91], v182 offset:320
	s_waitcnt vmcnt(13) lgkmcnt(0)
	v_mfma_f32_32x32x16_bf16 v[48:63], v[84:87], v[88:91], v[48:63]
	ds_read_b128 v[88:91], v182 offset:17216
	s_waitcnt lgkmcnt(0)
	v_mfma_f32_32x32x16_bf16 v[32:47], v[84:87], v[88:91], v[32:47]
	ds_read_b128 v[88:91], v182 offset:34112
	s_waitcnt lgkmcnt(0)
	v_mfma_f32_32x32x16_bf16 v[16:31], v[84:87], v[88:91], v[16:31]
	ds_read_b128 v[88:91], v182 offset:51008
	s_waitcnt lgkmcnt(0)
	v_mfma_f32_32x32x16_bf16 v[0:15], v[84:87], v[88:91], v[0:15]
	ds_read_b128 v[84:87], v182 offset:352
	s_waitcnt vmcnt(12) lgkmcnt(0)
	v_mfma_f32_32x32x16_bf16 v[48:63], v[80:83], v[84:87], v[48:63]
	ds_read_b128 v[84:87], v182 offset:17248
	s_waitcnt lgkmcnt(0)
	v_mfma_f32_32x32x16_bf16 v[32:47], v[80:83], v[84:87], v[32:47]
	ds_read_b128 v[84:87], v182 offset:34144
	s_waitcnt lgkmcnt(0)
	v_mfma_f32_32x32x16_bf16 v[16:31], v[80:83], v[84:87], v[16:31]
	ds_read_b128 v[84:87], v182 offset:51040
	s_waitcnt lgkmcnt(0)
	v_mfma_f32_32x32x16_bf16 v[0:15], v[80:83], v[84:87], v[0:15]
	ds_read_b128 v[80:83], v182 offset:384
	s_waitcnt vmcnt(11) lgkmcnt(0)
	v_mfma_f32_32x32x16_bf16 v[48:63], v[76:79], v[80:83], v[48:63]
	ds_read_b128 v[80:83], v182 offset:17280
	s_waitcnt lgkmcnt(0)
	v_mfma_f32_32x32x16_bf16 v[32:47], v[76:79], v[80:83], v[32:47]
	ds_read_b128 v[80:83], v182 offset:34176
	s_waitcnt lgkmcnt(0)
	v_mfma_f32_32x32x16_bf16 v[16:31], v[76:79], v[80:83], v[16:31]
	ds_read_b128 v[80:83], v182 offset:51072
	s_waitcnt lgkmcnt(0)
	v_mfma_f32_32x32x16_bf16 v[0:15], v[76:79], v[80:83], v[0:15]
	ds_read_b128 v[76:79], v182 offset:416
	s_waitcnt vmcnt(10) lgkmcnt(0)
	v_mfma_f32_32x32x16_bf16 v[48:63], v[72:75], v[76:79], v[48:63]
	ds_read_b128 v[76:79], v182 offset:17312
	s_waitcnt lgkmcnt(0)
	v_mfma_f32_32x32x16_bf16 v[32:47], v[72:75], v[76:79], v[32:47]
	ds_read_b128 v[76:79], v182 offset:34208
	s_waitcnt lgkmcnt(0)
	v_mfma_f32_32x32x16_bf16 v[16:31], v[72:75], v[76:79], v[16:31]
	ds_read_b128 v[76:79], v182 offset:51104
	s_waitcnt lgkmcnt(0)
	v_mfma_f32_32x32x16_bf16 v[0:15], v[72:75], v[76:79], v[0:15]
	ds_read_b128 v[72:75], v182 offset:448
	s_waitcnt vmcnt(9) lgkmcnt(0)
	v_mfma_f32_32x32x16_bf16 v[48:63], v[68:71], v[72:75], v[48:63]
	ds_read_b128 v[72:75], v182 offset:17344
	s_waitcnt lgkmcnt(0)
	v_mfma_f32_32x32x16_bf16 v[32:47], v[68:71], v[72:75], v[32:47]
	ds_read_b128 v[72:75], v182 offset:34240
	s_waitcnt lgkmcnt(0)
	v_mfma_f32_32x32x16_bf16 v[16:31], v[68:71], v[72:75], v[16:31]
	ds_read_b128 v[72:75], v182 offset:51136
	s_waitcnt lgkmcnt(0)
	v_mfma_f32_32x32x16_bf16 v[0:15], v[68:71], v[72:75], v[0:15]
	ds_read_b128 v[68:71], v182 offset:480
	s_waitcnt vmcnt(8) lgkmcnt(0)
	v_mfma_f32_32x32x16_bf16 v[48:63], v[64:67], v[68:71], v[48:63]
	ds_read_b128 v[68:71], v182 offset:17376
	s_waitcnt lgkmcnt(0)
	v_mfma_f32_32x32x16_bf16 v[32:47], v[64:67], v[68:71], v[32:47]
	ds_read_b128 v[68:71], v182 offset:34272
	s_waitcnt lgkmcnt(0)
	v_mfma_f32_32x32x16_bf16 v[16:31], v[64:67], v[68:71], v[16:31]
	ds_read_b128 v[68:71], v182 offset:51168
	s_waitcnt lgkmcnt(0)
	v_mfma_f32_32x32x16_bf16 v[0:15], v[64:67], v[68:71], v[0:15]
	ds_read_b128 v[64:67], v197
	ds_read_b128 v[68:71], v197 offset:32
	s_waitcnt vmcnt(7) lgkmcnt(1)
	v_mfma_f32_32x32x16_bf16 v[48:63], v[152:155], v[64:67], v[48:63]
	ds_read_b128 v[64:67], v197 offset:16896
	s_waitcnt lgkmcnt(0)
	v_mfma_f32_32x32x16_bf16 v[32:47], v[152:155], v[64:67], v[32:47]
	ds_read_b128 v[64:67], v197 offset:33792
	s_waitcnt lgkmcnt(0)
	v_mfma_f32_32x32x16_bf16 v[16:31], v[152:155], v[64:67], v[16:31]
	ds_read_b128 v[64:67], v197 offset:50688
	s_waitcnt lgkmcnt(0)
	v_mfma_f32_32x32x16_bf16 v[0:15], v[152:155], v[64:67], v[0:15]
	ds_read_b128 v[64:67], v197 offset:16928
	s_waitcnt vmcnt(6) lgkmcnt(0)
	v_mfma_f32_32x32x16_bf16 v[32:47], v[148:151], v[64:67], v[32:47]
	ds_read_b128 v[64:67], v197 offset:33824
	s_waitcnt lgkmcnt(0)
	v_mfma_f32_32x32x16_bf16 v[16:31], v[148:151], v[64:67], v[16:31]
	ds_read_b128 v[64:67], v197 offset:50720
	v_mfma_f32_32x32x16_bf16 v[48:63], v[148:151], v[68:71], v[48:63]
	s_waitcnt lgkmcnt(0)
	v_mfma_f32_32x32x16_bf16 v[0:15], v[148:151], v[64:67], v[0:15]
	ds_read_b128 v[64:67], v197 offset:64
	s_waitcnt vmcnt(5) lgkmcnt(0)
	v_mfma_f32_32x32x16_bf16 v[48:63], v[144:147], v[64:67], v[48:63]
	ds_read_b128 v[64:67], v197 offset:16960
	s_waitcnt lgkmcnt(0)
	v_mfma_f32_32x32x16_bf16 v[32:47], v[144:147], v[64:67], v[32:47]
	ds_read_b128 v[64:67], v197 offset:33856
	s_waitcnt lgkmcnt(0)
	v_mfma_f32_32x32x16_bf16 v[16:31], v[144:147], v[64:67], v[16:31]
	ds_read_b128 v[64:67], v197 offset:50752
	s_waitcnt lgkmcnt(0)
	v_mfma_f32_32x32x16_bf16 v[0:15], v[144:147], v[64:67], v[0:15]
	ds_read_b128 v[64:67], v197 offset:96
	s_waitcnt vmcnt(4) lgkmcnt(0)
	v_mfma_f32_32x32x16_bf16 v[48:63], v[140:143], v[64:67], v[48:63]
	ds_read_b128 v[64:67], v197 offset:16992
	s_waitcnt lgkmcnt(0)
	v_mfma_f32_32x32x16_bf16 v[32:47], v[140:143], v[64:67], v[32:47]
	ds_read_b128 v[64:67], v197 offset:33888
	s_waitcnt lgkmcnt(0)
	v_mfma_f32_32x32x16_bf16 v[16:31], v[140:143], v[64:67], v[16:31]
	ds_read_b128 v[64:67], v197 offset:50784
	s_waitcnt lgkmcnt(0)
; #define LAS __attribute__((address_space(3)))
; #define MFMA32(a, b, c) __builtin_amdgcn_mfma_f32_32x32x16_bf16((a), (b), (c), 0, 0, 0)
; DI unsigned pk2(float lo, float hi) { const f32x2 v = {lo, hi}; return __builtin_bit_cast(unsigned, __builtin_convertvector(v, bf16v2)); }
; DI float frcp(float x) { return __builtin_amdgcn_rcpf(x); }
; DI float gelu_tanh(float x) {
;     const float t = 0.7978845608028654f * (x + 0.044715f * x * x * x);
;     const float e = __expf(2.f * t);
;     const float th = 1.f - 2.f * frcp(e + 1.f);
;     return 0.5f * x * (1.f + th);
; }
; DI void ssm_prompt_unit(LAS unsigned char* lds, int unit, int tid, int l, const bf16_t* U, const bf16_t* mats_l, const float* lam16_l, bf16_t* Z, float* outr_l, float* outi_l) {
;     ...
;         for (int ks = 0; ks < 8; ++ks) {
;             const bf16x8 af = cfr[ks];
; #pragma unroll
;             for (int mt = 0; mt < 4; ++mt) { const bf16x8 bf = *(const LAS bf16x8*)(lds + SH_OFF + (mt * 32 + l32) * UP_PITCH + (16 * ks + 8 * h) * 2); acc[mt] = MFMA32(af, bf, acc[mt]); }
;         }
;         __syncthreads();
; #pragma unroll
;         for (int mt = 0; mt < 4; ++mt)
; #pragma unroll
;             for (int g4 = 0; g4 < 4; ++g4) {
;                 const int tok = 16 * (mt * 32 + l32) + 2 * wave + (g4 >> 1), c0 = 8 * (g4 & 1) + 4 * h;
;                 u32x2 w; w.x = pk2(gelu_tanh(acc[mt][4 * g4]), gelu_tanh(acc[mt][4 * g4 + 1])); w.y = pk2(gelu_tanh(acc[mt][4 * g4 + 2]), gelu_tanh(acc[mt][4 * g4 + 3]));
	v_mfma_f32_32x32x16_bf16 v[0:15], v[140:143], v[64:67], v[0:15]
	ds_read_b128 v[64:67], v197 offset:128
	s_waitcnt vmcnt(3) lgkmcnt(0)
	v_mfma_f32_32x32x16_bf16 v[48:63], v[136:139], v[64:67], v[48:63]
	ds_read_b128 v[64:67], v197 offset:17024
	s_waitcnt lgkmcnt(0)
	v_mfma_f32_32x32x16_bf16 v[32:47], v[136:139], v[64:67], v[32:47]
	ds_read_b128 v[64:67], v197 offset:33920
	s_waitcnt lgkmcnt(0)
	v_mfma_f32_32x32x16_bf16 v[16:31], v[136:139], v[64:67], v[16:31]
	ds_read_b128 v[64:67], v197 offset:50816
	s_waitcnt lgkmcnt(0)
	v_mfma_f32_32x32x16_bf16 v[0:15], v[136:139], v[64:67], v[0:15]
	ds_read_b128 v[64:67], v197 offset:160
	s_waitcnt vmcnt(2) lgkmcnt(0)
	v_mfma_f32_32x32x16_bf16 v[48:63], v[132:135], v[64:67], v[48:63]
	ds_read_b128 v[64:67], v197 offset:17056
	s_waitcnt lgkmcnt(0)
	v_mfma_f32_32x32x16_bf16 v[32:47], v[132:135], v[64:67], v[32:47]
	ds_read_b128 v[64:67], v197 offset:33952
	s_waitcnt lgkmcnt(0)
	v_mfma_f32_32x32x16_bf16 v[16:31], v[132:135], v[64:67], v[16:31]
	ds_read_b128 v[64:67], v197 offset:50848
	s_waitcnt lgkmcnt(0)
	v_mfma_f32_32x32x16_bf16 v[0:15], v[132:135], v[64:67], v[0:15]
	ds_read_b128 v[64:67], v197 offset:192
	s_waitcnt vmcnt(1) lgkmcnt(0)
	v_mfma_f32_32x32x16_bf16 v[48:63], v[128:131], v[64:67], v[48:63]
	ds_read_b128 v[64:67], v197 offset:17088
	s_waitcnt lgkmcnt(0)
	v_mfma_f32_32x32x16_bf16 v[32:47], v[128:131], v[64:67], v[32:47]
	ds_read_b128 v[64:67], v197 offset:33984
	s_waitcnt lgkmcnt(0)
	v_mfma_f32_32x32x16_bf16 v[16:31], v[128:131], v[64:67], v[16:31]
	ds_read_b128 v[64:67], v197 offset:50880
	s_waitcnt lgkmcnt(0)
	v_mfma_f32_32x32x16_bf16 v[0:15], v[128:131], v[64:67], v[0:15]
	ds_read_b128 v[64:67], v197 offset:224
	s_waitcnt vmcnt(0) lgkmcnt(0)
	v_mfma_f32_32x32x16_bf16 v[48:63], v[124:127], v[64:67], v[48:63]
	ds_read_b128 v[64:67], v197 offset:17120
	s_waitcnt lgkmcnt(0)
	v_mfma_f32_32x32x16_bf16 v[32:47], v[124:127], v[64:67], v[32:47]
	ds_read_b128 v[64:67], v197 offset:34016
	s_waitcnt lgkmcnt(0)
	v_mfma_f32_32x32x16_bf16 v[16:31], v[124:127], v[64:67], v[16:31]
	ds_read_b128 v[64:67], v197 offset:50912
	s_waitcnt lgkmcnt(0)
	s_barrier
	v_mfma_f32_32x32x16_bf16 v[0:15], v[124:127], v[64:67], v[0:15]
	s_nop 1
	v_mul_f32_e32 v64, 0x3d372713, v48
	v_mul_f32_e32 v65, 0x3d372713, v49
	v_mul_f32_e32 v64, v48, v64
	v_mul_f32_e32 v65, v49, v65
	v_fma_f32 v64, v48, v64, v48
	v_fma_f32 v65, v49, v65, v49
	v_mul_f32_e32 v64, 0x3f4c422a, v64
	v_mul_f32_e32 v65, 0x3f4c422a, v65
	v_add_f32_e32 v64, v64, v64
	v_add_f32_e32 v65, v65, v65
	v_mul_f32_e32 v64, 0x3fb8aa3b, v64
	v_mul_f32_e32 v65, 0x3fb8aa3b, v65
	v_exp_f32_e32 v64, v64
	v_exp_f32_e32 v65, v65
	v_pk_mul_f32 v[48:49], v[48:49], 0.5 op_sel_hi:[1,0]
	v_add_f32_e32 v64, 1.0, v64
	v_add_f32_e32 v65, 1.0, v65
	v_rcp_f32_e32 v64, v64
	v_rcp_f32_e32 v65, v65
	s_nop 0
	v_pk_fma_f32 v[64:65], v[64:65], 2.0, 1.0 op_sel_hi:[1,0,0] neg_lo:[1,0,0] neg_hi:[1,0,0]
	s_nop 0
	v_pk_add_f32 v[64:65], v[64:65], 1.0 op_sel_hi:[1,0]
	s_nop 0
	v_pk_mul_f32 v[48:49], v[48:49], v[64:65]
	s_nop 0
	v_cvt_pk_bf16_f32 v48, v48, v49
	v_mul_f32_e32 v49, 0x3d372713, v50
	v_mul_f32_e32 v49, v50, v49
	v_fma_f32 v49, v50, v49, v50
	v_mul_f32_e32 v49, 0x3f4c422a, v49
	v_add_f32_e32 v49, v49, v49
	v_mul_f32_e32 v49, 0x3fb8aa3b, v49
	v_exp_f32_e32 v49, v49
	s_nop 0
	v_add_f32_e32 v49, 1.0, v49
	v_rcp_f32_e32 v64, v49
	v_mul_f32_e32 v49, 0x3d372713, v51
	v_mul_f32_e32 v49, v51, v49
	v_fma_f32 v49, v51, v49, v51
	v_mul_f32_e32 v49, 0x3f4c422a, v49
	v_add_f32_e32 v49, v49, v49
	v_mul_f32_e32 v49, 0x3fb8aa3b, v49
	v_exp_f32_e32 v49, v49
	v_pk_mul_f32 v[50:51], v[50:51], 0.5 op_sel_hi:[1,0]
	v_add_f32_e32 v49, 1.0, v49
	v_rcp_f32_e32 v65, v49
	s_nop 0
	v_pk_fma_f32 v[64:65], v[64:65], 2.0, 1.0 op_sel_hi:[1,0,0] neg_lo:[1,0,0] neg_hi:[1,0,0]
	s_nop 0
	v_pk_add_f32 v[64:65], v[64:65], 1.0 op_sel_hi:[1,0]
	s_nop 0
	v_pk_mul_f32 v[50:51], v[50:51], v[64:65]
	s_nop 0
	v_cvt_pk_bf16_f32 v49, v50, v51
	v_mul_f32_e32 v50, 0x3d372713, v52
	v_mul_f32_e32 v51, 0x3d372713, v53
	v_mul_f32_e32 v50, v52, v50
	v_mul_f32_e32 v51, v53, v51
	v_fma_f32 v50, v52, v50, v52
	v_fma_f32 v51, v53, v51, v53
	v_mul_f32_e32 v50, 0x3f4c422a, v50
	v_mul_f32_e32 v51, 0x3f4c422a, v51
	v_add_f32_e32 v50, v50, v50
	v_add_f32_e32 v51, v51, v51
	v_mul_f32_e32 v50, 0x3fb8aa3b, v50
	v_mul_f32_e32 v51, 0x3fb8aa3b, v51
	v_exp_f32_e32 v50, v50
	v_exp_f32_e32 v51, v51
	v_pk_mul_f32 v[52:53], v[52:53], 0.5 op_sel_hi:[1,0]
	v_add_f32_e32 v50, 1.0, v50
	v_add_f32_e32 v51, 1.0, v51
	v_rcp_f32_e32 v50, v50
	v_rcp_f32_e32 v51, v51
	s_nop 0
	v_pk_fma_f32 v[50:51], v[50:51], 2.0, 1.0 op_sel_hi:[1,0,0] neg_lo:[1,0,0] neg_hi:[1,0,0]
	s_nop 0
	v_pk_add_f32 v[50:51], v[50:51], 1.0 op_sel_hi:[1,0]
	s_nop 0
	v_pk_mul_f32 v[50:51], v[52:53], v[50:51]
	s_nop 0
	v_cvt_pk_bf16_f32 v50, v50, v51
	v_mul_f32_e32 v51, 0x3d372713, v54
	v_mul_f32_e32 v51, v54, v51
	v_fma_f32 v51, v54, v51, v54
	v_mul_f32_e32 v51, 0x3f4c422a, v51
	v_add_f32_e32 v51, v51, v51
	v_mul_f32_e32 v51, 0x3fb8aa3b, v51
	v_exp_f32_e32 v51, v51
	s_nop 0
	v_add_f32_e32 v51, 1.0, v51
	v_rcp_f32_e32 v52, v51
	v_mul_f32_e32 v51, 0x3d372713, v55
	v_mul_f32_e32 v51, v55, v51
	v_fma_f32 v51, v55, v51, v55
	v_mul_f32_e32 v51, 0x3f4c422a, v51
	v_add_f32_e32 v51, v51, v51
	v_mul_f32_e32 v51, 0x3fb8aa3b, v51
	v_exp_f32_e32 v51, v51
	v_pk_mul_f32 v[54:55], v[54:55], 0.5 op_sel_hi:[1,0]
	v_add_f32_e32 v51, 1.0, v51
	v_rcp_f32_e32 v53, v51
	s_nop 0
	v_pk_fma_f32 v[52:53], v[52:53], 2.0, 1.0 op_sel_hi:[1,0,0] neg_lo:[1,0,0] neg_hi:[1,0,0]
	s_nop 0
	v_pk_add_f32 v[52:53], v[52:53], 1.0 op_sel_hi:[1,0]
	s_nop 0
	v_pk_mul_f32 v[52:53], v[54:55], v[52:53]
	v_pk_mul_f32 v[54:55], v[62:63], 0.5 op_sel_hi:[1,0]
; #define LAS __attribute__((address_space(3)))
; DI unsigned pk2(float lo, float hi) { const f32x2 v = {lo, hi}; return __builtin_bit_cast(unsigned, __builtin_convertvector(v, bf16v2)); }
; DI float frcp(float x) { return __builtin_amdgcn_rcpf(x); }
; DI float gelu_tanh(float x) {
;     const float t = 0.7978845608028654f * (x + 0.044715f * x * x * x);
;     const float e = __expf(2.f * t);
;     const float th = 1.f - 2.f * frcp(e + 1.f);
;     return 0.5f * x * (1.f + th);
; }
; DI void ssm_prompt_unit(LAS unsigned char* lds, int unit, int tid, int l, const bf16_t* U, const bf16_t* mats_l, const float* lam16_l, bf16_t* Z, float* outr_l, float* outi_l) {
;     ...
; #pragma unroll
;         for (int mt = 0; mt < 4; ++mt)
; #pragma unroll
;             for (int g4 = 0; g4 < 4; ++g4) {
;                 const int tok = 16 * (mt * 32 + l32) + 2 * wave + (g4 >> 1), c0 = 8 * (g4 & 1) + 4 * h;
;                 u32x2 w; w.x = pk2(gelu_tanh(acc[mt][4 * g4]), gelu_tanh(acc[mt][4 * g4 + 1])); w.y = pk2(gelu_tanh(acc[mt][4 * g4 + 2]), gelu_tanh(acc[mt][4 * g4 + 3]));
;                 *(LAS u32x2*)(lds + tok * 32 + c0 * 2) = w;
	v_cvt_pk_bf16_f32 v51, v52, v53
	ds_write2_b64 v198, v[48:49], v[50:51] offset1:2
	v_mul_f32_e32 v48, 0x3d372713, v56
	v_mul_f32_e32 v49, 0x3d372713, v57
	v_mul_f32_e32 v48, v56, v48
	v_mul_f32_e32 v49, v57, v49
	v_fma_f32 v48, v56, v48, v56
	v_fma_f32 v49, v57, v49, v57
	v_mul_f32_e32 v48, 0x3f4c422a, v48
	v_mul_f32_e32 v49, 0x3f4c422a, v49
	v_add_f32_e32 v48, v48, v48
	v_add_f32_e32 v49, v49, v49
	v_mul_f32_e32 v48, 0x3fb8aa3b, v48
	v_mul_f32_e32 v49, 0x3fb8aa3b, v49
	v_exp_f32_e32 v48, v48
	v_exp_f32_e32 v49, v49
	v_pk_mul_f32 v[50:51], v[56:57], 0.5 op_sel_hi:[1,0]
	v_pk_mul_f32 v[52:53], v[58:59], 0.5 op_sel_hi:[1,0]
	v_add_f32_e32 v48, 1.0, v48
	v_add_f32_e32 v49, 1.0, v49
	v_rcp_f32_e32 v48, v48
	v_rcp_f32_e32 v49, v49
	s_nop 0
	v_pk_fma_f32 v[48:49], v[48:49], 2.0, 1.0 op_sel_hi:[1,0,0] neg_lo:[1,0,0] neg_hi:[1,0,0]
	s_nop 0
	v_pk_add_f32 v[48:49], v[48:49], 1.0 op_sel_hi:[1,0]
	s_nop 0
	v_pk_mul_f32 v[48:49], v[50:51], v[48:49]
	s_nop 0
	v_cvt_pk_bf16_f32 v48, v48, v49
	v_mul_f32_e32 v49, 0x3d372713, v58
	v_mul_f32_e32 v49, v58, v49
	v_fma_f32 v49, v58, v49, v58
	v_mul_f32_e32 v49, 0x3f4c422a, v49
	v_add_f32_e32 v49, v49, v49
	v_mul_f32_e32 v49, 0x3fb8aa3b, v49
	v_exp_f32_e32 v49, v49
	s_nop 0
	v_add_f32_e32 v49, 1.0, v49
	v_rcp_f32_e32 v50, v49
	v_mul_f32_e32 v49, 0x3d372713, v59
	v_mul_f32_e32 v49, v59, v49
	v_fma_f32 v49, v59, v49, v59
	v_mul_f32_e32 v49, 0x3f4c422a, v49
	v_add_f32_e32 v49, v49, v49
	v_mul_f32_e32 v49, 0x3fb8aa3b, v49
	v_exp_f32_e32 v49, v49
	s_nop 0
	v_add_f32_e32 v49, 1.0, v49
	v_rcp_f32_e32 v51, v49
	s_nop 0
	v_pk_fma_f32 v[50:51], v[50:51], 2.0, 1.0 op_sel_hi:[1,0,0] neg_lo:[1,0,0] neg_hi:[1,0,0]
	s_nop 0
	v_pk_add_f32 v[50:51], v[50:51], 1.0 op_sel_hi:[1,0]
	s_nop 0
	v_pk_mul_f32 v[50:51], v[52:53], v[50:51]
	v_pk_mul_f32 v[52:53], v[60:61], 0.5 op_sel_hi:[1,0]
	v_cvt_pk_bf16_f32 v49, v50, v51
	v_mul_f32_e32 v50, 0x3d372713, v60
	v_mul_f32_e32 v51, 0x3d372713, v61
	v_mul_f32_e32 v50, v60, v50
	v_mul_f32_e32 v51, v61, v51
	v_fma_f32 v50, v60, v50, v60
	v_fma_f32 v51, v61, v51, v61
	v_mul_f32_e32 v50, 0x3f4c422a, v50
	v_mul_f32_e32 v51, 0x3f4c422a, v51
	v_add_f32_e32 v50, v50, v50
	v_add_f32_e32 v51, v51, v51
	v_mul_f32_e32 v50, 0x3fb8aa3b, v50
	v_mul_f32_e32 v51, 0x3fb8aa3b, v51
	v_exp_f32_e32 v50, v50
	v_exp_f32_e32 v51, v51
	v_add_f32_e32 v50, 1.0, v50
	v_add_f32_e32 v51, 1.0, v51
	v_rcp_f32_e32 v50, v50
	v_rcp_f32_e32 v51, v51
	s_nop 0
	v_pk_fma_f32 v[50:51], v[50:51], 2.0, 1.0 op_sel_hi:[1,0,0] neg_lo:[1,0,0] neg_hi:[1,0,0]
	s_nop 0
	v_pk_add_f32 v[50:51], v[50:51], 1.0 op_sel_hi:[1,0]
	s_nop 0
	v_pk_mul_f32 v[50:51], v[52:53], v[50:51]
	s_nop 0
	v_cvt_pk_bf16_f32 v50, v50, v51
	v_mul_f32_e32 v51, 0x3d372713, v62
	v_mul_f32_e32 v51, v62, v51
	v_fma_f32 v51, v62, v51, v62
	v_mul_f32_e32 v51, 0x3f4c422a, v51
	v_add_f32_e32 v51, v51, v51
	v_mul_f32_e32 v51, 0x3fb8aa3b, v51
	v_exp_f32_e32 v51, v51
	s_nop 0
	v_add_f32_e32 v51, 1.0, v51
	v_rcp_f32_e32 v52, v51
	v_mul_f32_e32 v51, 0x3d372713, v63
	v_mul_f32_e32 v51, v63, v51
	v_fma_f32 v51, v63, v51, v63
	v_mul_f32_e32 v51, 0x3f4c422a, v51
	v_add_f32_e32 v51, v51, v51
	v_mul_f32_e32 v51, 0x3fb8aa3b, v51
	v_exp_f32_e32 v51, v51
	s_nop 0
	v_add_f32_e32 v51, 1.0, v51
	v_rcp_f32_e32 v53, v51
	s_nop 0
	v_pk_fma_f32 v[52:53], v[52:53], 2.0, 1.0 op_sel_hi:[1,0,0] neg_lo:[1,0,0] neg_hi:[1,0,0]
	s_nop 0
	v_pk_add_f32 v[52:53], v[52:53], 1.0 op_sel_hi:[1,0]
	s_nop 0
	v_pk_mul_f32 v[52:53], v[54:55], v[52:53]
	s_nop 0
	v_cvt_pk_bf16_f32 v51, v52, v53
	ds_write2_b64 v198, v[48:49], v[50:51] offset0:4 offset1:6
	v_mul_f32_e32 v48, 0x3d372713, v32
	v_mul_f32_e32 v49, 0x3d372713, v33
	v_mul_f32_e32 v48, v32, v48
	v_mul_f32_e32 v49, v33, v49
	v_fma_f32 v48, v32, v48, v32
	v_fma_f32 v49, v33, v49, v33
	v_mul_f32_e32 v48, 0x3f4c422a, v48
	v_mul_f32_e32 v49, 0x3f4c422a, v49
	v_add_f32_e32 v48, v48, v48
	v_add_f32_e32 v49, v49, v49
	v_mul_f32_e32 v48, 0x3fb8aa3b, v48
	v_mul_f32_e32 v49, 0x3fb8aa3b, v49
	v_exp_f32_e32 v48, v48
	v_exp_f32_e32 v49, v49
	v_pk_mul_f32 v[32:33], v[32:33], 0.5 op_sel_hi:[1,0]
	v_add_f32_e32 v48, 1.0, v48
	v_add_f32_e32 v49, 1.0, v49
	v_rcp_f32_e32 v48, v48
	v_rcp_f32_e32 v49, v49
	s_nop 0
	v_pk_fma_f32 v[48:49], v[48:49], 2.0, 1.0 op_sel_hi:[1,0,0] neg_lo:[1,0,0] neg_hi:[1,0,0]
	s_nop 0
	v_pk_add_f32 v[48:49], v[48:49], 1.0 op_sel_hi:[1,0]
	s_nop 0
	v_pk_mul_f32 v[32:33], v[32:33], v[48:49]
	s_nop 0
	v_cvt_pk_bf16_f32 v32, v32, v33
	v_mul_f32_e32 v33, 0x3d372713, v34
	v_mul_f32_e32 v33, v34, v33
	v_fma_f32 v33, v34, v33, v34
	v_mul_f32_e32 v33, 0x3f4c422a, v33
	v_add_f32_e32 v33, v33, v33
	v_mul_f32_e32 v33, 0x3fb8aa3b, v33
	v_exp_f32_e32 v33, v33
	s_nop 0
	v_add_f32_e32 v33, 1.0, v33
	v_rcp_f32_e32 v48, v33
	v_mul_f32_e32 v33, 0x3d372713, v35
	v_mul_f32_e32 v33, v35, v33
	v_fma_f32 v33, v35, v33, v35
	v_mul_f32_e32 v33, 0x3f4c422a, v33
	v_add_f32_e32 v33, v33, v33
	v_mul_f32_e32 v33, 0x3fb8aa3b, v33
	v_exp_f32_e32 v33, v33
	v_pk_mul_f32 v[34:35], v[34:35], 0.5 op_sel_hi:[1,0]
	v_add_f32_e32 v33, 1.0, v33
	v_rcp_f32_e32 v49, v33
	s_nop 0
	v_pk_fma_f32 v[48:49], v[48:49], 2.0, 1.0 op_sel_hi:[1,0,0] neg_lo:[1,0,0] neg_hi:[1,0,0]
	s_nop 0
	v_pk_add_f32 v[48:49], v[48:49], 1.0 op_sel_hi:[1,0]
	s_nop 0
	v_pk_mul_f32 v[34:35], v[34:35], v[48:49]
	v_add_u32_e32 v48, 0x4200, v198
	v_cvt_pk_bf16_f32 v33, v34, v35
	v_mul_f32_e32 v34, 0x3d372713, v36
	v_mul_f32_e32 v35, 0x3d372713, v37
	v_mul_f32_e32 v34, v36, v34
	v_mul_f32_e32 v35, v37, v35
	v_fma_f32 v34, v36, v34, v36
	v_fma_f32 v35, v37, v35, v37
	v_mul_f32_e32 v34, 0x3f4c422a, v34
	v_mul_f32_e32 v35, 0x3f4c422a, v35
	v_add_f32_e32 v34, v34, v34
	v_add_f32_e32 v35, v35, v35
	v_mul_f32_e32 v34, 0x3fb8aa3b, v34
; #define LAS __attribute__((address_space(3)))
; DI unsigned pk2(float lo, float hi) { const f32x2 v = {lo, hi}; return __builtin_bit_cast(unsigned, __builtin_convertvector(v, bf16v2)); }
; DI float frcp(float x) { return __builtin_amdgcn_rcpf(x); }
; DI float gelu_tanh(float x) {
;     const float t = 0.7978845608028654f * (x + 0.044715f * x * x * x);
;     const float e = __expf(2.f * t);
;     const float th = 1.f - 2.f * frcp(e + 1.f);
;     return 0.5f * x * (1.f + th);
; }
; DI void ssm_prompt_unit(LAS unsigned char* lds, int unit, int tid, int l, const bf16_t* U, const bf16_t* mats_l, const float* lam16_l, bf16_t* Z, float* outr_l, float* outi_l) {
;     ...
; #pragma unroll
;         for (int mt = 0; mt < 4; ++mt)
; #pragma unroll
;             for (int g4 = 0; g4 < 4; ++g4) {
;                 const int tok = 16 * (mt * 32 + l32) + 2 * wave + (g4 >> 1), c0 = 8 * (g4 & 1) + 4 * h;
;                 u32x2 w; w.x = pk2(gelu_tanh(acc[mt][4 * g4]), gelu_tanh(acc[mt][4 * g4 + 1])); w.y = pk2(gelu_tanh(acc[mt][4 * g4 + 2]), gelu_tanh(acc[mt][4 * g4 + 3]));
;                 *(LAS u32x2*)(lds + tok * 32 + c0 * 2) = w;
	v_mul_f32_e32 v35, 0x3fb8aa3b, v35
	v_exp_f32_e32 v34, v34
	v_exp_f32_e32 v35, v35
	v_pk_mul_f32 v[36:37], v[36:37], 0.5 op_sel_hi:[1,0]
	v_add_f32_e32 v34, 1.0, v34
	v_add_f32_e32 v35, 1.0, v35
	v_rcp_f32_e32 v34, v34
	v_rcp_f32_e32 v35, v35
	s_nop 0
	v_pk_fma_f32 v[34:35], v[34:35], 2.0, 1.0 op_sel_hi:[1,0,0] neg_lo:[1,0,0] neg_hi:[1,0,0]
	s_nop 0
	v_pk_add_f32 v[34:35], v[34:35], 1.0 op_sel_hi:[1,0]
	s_nop 0
	v_pk_mul_f32 v[34:35], v[36:37], v[34:35]
	s_nop 0
	v_cvt_pk_bf16_f32 v34, v34, v35
	v_mul_f32_e32 v35, 0x3d372713, v38
	v_mul_f32_e32 v35, v38, v35
	v_fma_f32 v35, v38, v35, v38
	v_mul_f32_e32 v35, 0x3f4c422a, v35
	v_add_f32_e32 v35, v35, v35
	v_mul_f32_e32 v35, 0x3fb8aa3b, v35
	v_exp_f32_e32 v35, v35
	s_nop 0
	v_add_f32_e32 v35, 1.0, v35
	v_rcp_f32_e32 v36, v35
	v_mul_f32_e32 v35, 0x3d372713, v39
	v_mul_f32_e32 v35, v39, v35
	v_fma_f32 v35, v39, v35, v39
	v_mul_f32_e32 v35, 0x3f4c422a, v35
	v_add_f32_e32 v35, v35, v35
	v_mul_f32_e32 v35, 0x3fb8aa3b, v35
	v_exp_f32_e32 v35, v35
	v_pk_mul_f32 v[38:39], v[38:39], 0.5 op_sel_hi:[1,0]
	v_add_f32_e32 v35, 1.0, v35
	v_rcp_f32_e32 v37, v35
	s_nop 0
	v_pk_fma_f32 v[36:37], v[36:37], 2.0, 1.0 op_sel_hi:[1,0,0] neg_lo:[1,0,0] neg_hi:[1,0,0]
	s_nop 0
	v_pk_add_f32 v[36:37], v[36:37], 1.0 op_sel_hi:[1,0]
	s_nop 0
	v_pk_mul_f32 v[36:37], v[38:39], v[36:37]
	v_pk_mul_f32 v[38:39], v[46:47], 0.5 op_sel_hi:[1,0]
	v_cvt_pk_bf16_f32 v35, v36, v37
	ds_write2_b64 v48, v[32:33], v[34:35] offset1:2
	v_mul_f32_e32 v32, 0x3d372713, v40
	v_mul_f32_e32 v33, 0x3d372713, v41
	v_mul_f32_e32 v32, v40, v32
	v_mul_f32_e32 v33, v41, v33
	v_fma_f32 v32, v40, v32, v40
	v_fma_f32 v33, v41, v33, v41
	v_mul_f32_e32 v32, 0x3f4c422a, v32
	v_mul_f32_e32 v33, 0x3f4c422a, v33
	v_add_f32_e32 v32, v32, v32
	v_add_f32_e32 v33, v33, v33
	v_mul_f32_e32 v32, 0x3fb8aa3b, v32
	v_mul_f32_e32 v33, 0x3fb8aa3b, v33
	v_exp_f32_e32 v32, v32
	v_exp_f32_e32 v33, v33
	v_pk_mul_f32 v[34:35], v[40:41], 0.5 op_sel_hi:[1,0]
	v_pk_mul_f32 v[36:37], v[42:43], 0.5 op_sel_hi:[1,0]
	v_add_f32_e32 v32, 1.0, v32
	v_add_f32_e32 v33, 1.0, v33
	v_rcp_f32_e32 v32, v32
	v_rcp_f32_e32 v33, v33
	s_nop 0
	v_pk_fma_f32 v[32:33], v[32:33], 2.0, 1.0 op_sel_hi:[1,0,0] neg_lo:[1,0,0] neg_hi:[1,0,0]
	s_nop 0
	v_pk_add_f32 v[32:33], v[32:33], 1.0 op_sel_hi:[1,0]
	s_nop 0
	v_pk_mul_f32 v[32:33], v[34:35], v[32:33]
	s_nop 0
	v_cvt_pk_bf16_f32 v32, v32, v33
	v_mul_f32_e32 v33, 0x3d372713, v42
	v_mul_f32_e32 v33, v42, v33
	v_fma_f32 v33, v42, v33, v42
	v_mul_f32_e32 v33, 0x3f4c422a, v33
	v_add_f32_e32 v33, v33, v33
	v_mul_f32_e32 v33, 0x3fb8aa3b, v33
	v_exp_f32_e32 v33, v33
	s_nop 0
	v_add_f32_e32 v33, 1.0, v33
	v_rcp_f32_e32 v34, v33
	v_mul_f32_e32 v33, 0x3d372713, v43
	v_mul_f32_e32 v33, v43, v33
	v_fma_f32 v33, v43, v33, v43
	v_mul_f32_e32 v33, 0x3f4c422a, v33
	v_add_f32_e32 v33, v33, v33
	v_mul_f32_e32 v33, 0x3fb8aa3b, v33
	v_exp_f32_e32 v33, v33
	s_nop 0
	v_add_f32_e32 v33, 1.0, v33
	v_rcp_f32_e32 v35, v33
	s_nop 0
	v_pk_fma_f32 v[34:35], v[34:35], 2.0, 1.0 op_sel_hi:[1,0,0] neg_lo:[1,0,0] neg_hi:[1,0,0]
	s_nop 0
	v_pk_add_f32 v[34:35], v[34:35], 1.0 op_sel_hi:[1,0]
	s_nop 0
	v_pk_mul_f32 v[34:35], v[36:37], v[34:35]
	v_pk_mul_f32 v[36:37], v[44:45], 0.5 op_sel_hi:[1,0]
	v_cvt_pk_bf16_f32 v33, v34, v35
	v_mul_f32_e32 v34, 0x3d372713, v44
	v_mul_f32_e32 v35, 0x3d372713, v45
	v_mul_f32_e32 v34, v44, v34
	v_mul_f32_e32 v35, v45, v35
	v_fma_f32 v34, v44, v34, v44
	v_fma_f32 v35, v45, v35, v45
	v_mul_f32_e32 v34, 0x3f4c422a, v34
	v_mul_f32_e32 v35, 0x3f4c422a, v35
	v_add_f32_e32 v34, v34, v34
	v_add_f32_e32 v35, v35, v35
	v_mul_f32_e32 v34, 0x3fb8aa3b, v34
	v_mul_f32_e32 v35, 0x3fb8aa3b, v35
	v_exp_f32_e32 v34, v34
	v_exp_f32_e32 v35, v35
	v_add_f32_e32 v34, 1.0, v34
	v_add_f32_e32 v35, 1.0, v35
	v_rcp_f32_e32 v34, v34
	v_rcp_f32_e32 v35, v35
	s_nop 0
	v_pk_fma_f32 v[34:35], v[34:35], 2.0, 1.0 op_sel_hi:[1,0,0] neg_lo:[1,0,0] neg_hi:[1,0,0]
	s_nop 0
	v_pk_add_f32 v[34:35], v[34:35], 1.0 op_sel_hi:[1,0]
	s_nop 0
	v_pk_mul_f32 v[34:35], v[36:37], v[34:35]
	s_nop 0
	v_cvt_pk_bf16_f32 v34, v34, v35
	v_mul_f32_e32 v35, 0x3d372713, v46
	v_mul_f32_e32 v35, v46, v35
	v_fma_f32 v35, v46, v35, v46
	v_mul_f32_e32 v35, 0x3f4c422a, v35
	v_add_f32_e32 v35, v35, v35
	v_mul_f32_e32 v35, 0x3fb8aa3b, v35
	v_exp_f32_e32 v35, v35
	s_nop 0
	v_add_f32_e32 v35, 1.0, v35
	v_rcp_f32_e32 v36, v35
	v_mul_f32_e32 v35, 0x3d372713, v47
	v_mul_f32_e32 v35, v47, v35
	v_fma_f32 v35, v47, v35, v47
	v_mul_f32_e32 v35, 0x3f4c422a, v35
	v_add_f32_e32 v35, v35, v35
	v_mul_f32_e32 v35, 0x3fb8aa3b, v35
	v_exp_f32_e32 v35, v35
	s_nop 0
	v_add_f32_e32 v35, 1.0, v35
	v_rcp_f32_e32 v37, v35
	s_nop 0
	v_pk_fma_f32 v[36:37], v[36:37], 2.0, 1.0 op_sel_hi:[1,0,0] neg_lo:[1,0,0] neg_hi:[1,0,0]
	s_nop 0
	v_pk_add_f32 v[36:37], v[36:37], 1.0 op_sel_hi:[1,0]
	s_nop 0
	v_pk_mul_f32 v[36:37], v[38:39], v[36:37]
	s_nop 0
	v_cvt_pk_bf16_f32 v35, v36, v37
	ds_write2_b64 v48, v[32:33], v[34:35] offset0:4 offset1:6
	v_mul_f32_e32 v32, 0x3d372713, v16
	v_mul_f32_e32 v33, 0x3d372713, v17
	v_mul_f32_e32 v32, v16, v32
	v_mul_f32_e32 v33, v17, v33
	v_fma_f32 v32, v16, v32, v16
	v_fma_f32 v33, v17, v33, v17
	v_mul_f32_e32 v32, 0x3f4c422a, v32
	v_mul_f32_e32 v33, 0x3f4c422a, v33
	v_add_f32_e32 v32, v32, v32
	v_add_f32_e32 v33, v33, v33
	v_mul_f32_e32 v32, 0x3fb8aa3b, v32
	v_mul_f32_e32 v33, 0x3fb8aa3b, v33
	v_exp_f32_e32 v32, v32
	v_exp_f32_e32 v33, v33
	v_pk_mul_f32 v[16:17], v[16:17], 0.5 op_sel_hi:[1,0]
	v_add_f32_e32 v32, 1.0, v32
	v_add_f32_e32 v33, 1.0, v33
	v_rcp_f32_e32 v32, v32
	v_rcp_f32_e32 v33, v33
	s_nop 0
	v_pk_fma_f32 v[32:33], v[32:33], 2.0, 1.0 op_sel_hi:[1,0,0] neg_lo:[1,0,0] neg_hi:[1,0,0]
	s_nop 0
; #define LAS __attribute__((address_space(3)))
; DI unsigned pk2(float lo, float hi) { const f32x2 v = {lo, hi}; return __builtin_bit_cast(unsigned, __builtin_convertvector(v, bf16v2)); }
; DI float frcp(float x) { return __builtin_amdgcn_rcpf(x); }
; DI float gelu_tanh(float x) {
;     const float t = 0.7978845608028654f * (x + 0.044715f * x * x * x);
;     const float e = __expf(2.f * t);
;     const float th = 1.f - 2.f * frcp(e + 1.f);
;     return 0.5f * x * (1.f + th);
; }
; DI void ssm_prompt_unit(LAS unsigned char* lds, int unit, int tid, int l, const bf16_t* U, const bf16_t* mats_l, const float* lam16_l, bf16_t* Z, float* outr_l, float* outi_l) {
;     ...
; #pragma unroll
;         for (int mt = 0; mt < 4; ++mt)
; #pragma unroll
;             for (int g4 = 0; g4 < 4; ++g4) {
;                 const int tok = 16 * (mt * 32 + l32) + 2 * wave + (g4 >> 1), c0 = 8 * (g4 & 1) + 4 * h;
;                 u32x2 w; w.x = pk2(gelu_tanh(acc[mt][4 * g4]), gelu_tanh(acc[mt][4 * g4 + 1])); w.y = pk2(gelu_tanh(acc[mt][4 * g4 + 2]), gelu_tanh(acc[mt][4 * g4 + 3]));
;                 *(LAS u32x2*)(lds + tok * 32 + c0 * 2) = w;
	v_pk_add_f32 v[32:33], v[32:33], 1.0 op_sel_hi:[1,0]
	s_nop 0
	v_pk_mul_f32 v[16:17], v[16:17], v[32:33]
	s_nop 0
	v_cvt_pk_bf16_f32 v16, v16, v17
	v_mul_f32_e32 v17, 0x3d372713, v18
	v_mul_f32_e32 v17, v18, v17
	v_fma_f32 v17, v18, v17, v18
	v_mul_f32_e32 v17, 0x3f4c422a, v17
	v_add_f32_e32 v17, v17, v17
	v_mul_f32_e32 v17, 0x3fb8aa3b, v17
	v_exp_f32_e32 v17, v17
	s_nop 0
	v_add_f32_e32 v17, 1.0, v17
	v_rcp_f32_e32 v32, v17
	v_mul_f32_e32 v17, 0x3d372713, v19
	v_mul_f32_e32 v17, v19, v17
	v_fma_f32 v17, v19, v17, v19
	v_mul_f32_e32 v17, 0x3f4c422a, v17
	v_add_f32_e32 v17, v17, v17
	v_mul_f32_e32 v17, 0x3fb8aa3b, v17
	v_exp_f32_e32 v17, v17
	v_pk_mul_f32 v[18:19], v[18:19], 0.5 op_sel_hi:[1,0]
	v_add_f32_e32 v17, 1.0, v17
	v_rcp_f32_e32 v33, v17
	s_nop 0
	v_pk_fma_f32 v[32:33], v[32:33], 2.0, 1.0 op_sel_hi:[1,0,0] neg_lo:[1,0,0] neg_hi:[1,0,0]
	s_nop 0
	v_pk_add_f32 v[32:33], v[32:33], 1.0 op_sel_hi:[1,0]
	s_nop 0
	v_pk_mul_f32 v[18:19], v[18:19], v[32:33]
	v_add_u32_e32 v32, 0x8400, v198
	v_cvt_pk_bf16_f32 v17, v18, v19
	v_mul_f32_e32 v18, 0x3d372713, v20
	v_mul_f32_e32 v19, 0x3d372713, v21
	v_mul_f32_e32 v18, v20, v18
	v_mul_f32_e32 v19, v21, v19
	v_fma_f32 v18, v20, v18, v20
	v_fma_f32 v19, v21, v19, v21
	v_mul_f32_e32 v18, 0x3f4c422a, v18
	v_mul_f32_e32 v19, 0x3f4c422a, v19
	v_add_f32_e32 v18, v18, v18
	v_add_f32_e32 v19, v19, v19
	v_mul_f32_e32 v18, 0x3fb8aa3b, v18
	v_mul_f32_e32 v19, 0x3fb8aa3b, v19
	v_exp_f32_e32 v18, v18
	v_exp_f32_e32 v19, v19
	v_pk_mul_f32 v[20:21], v[20:21], 0.5 op_sel_hi:[1,0]
	v_add_f32_e32 v18, 1.0, v18
	v_add_f32_e32 v19, 1.0, v19
	v_rcp_f32_e32 v18, v18
	v_rcp_f32_e32 v19, v19
	s_nop 0
	v_pk_fma_f32 v[18:19], v[18:19], 2.0, 1.0 op_sel_hi:[1,0,0] neg_lo:[1,0,0] neg_hi:[1,0,0]
	s_nop 0
	v_pk_add_f32 v[18:19], v[18:19], 1.0 op_sel_hi:[1,0]
	s_nop 0
	v_pk_mul_f32 v[18:19], v[20:21], v[18:19]
	s_nop 0
	v_cvt_pk_bf16_f32 v18, v18, v19
	v_mul_f32_e32 v19, 0x3d372713, v22
	v_mul_f32_e32 v19, v22, v19
	v_fma_f32 v19, v22, v19, v22
	v_mul_f32_e32 v19, 0x3f4c422a, v19
	v_add_f32_e32 v19, v19, v19
	v_mul_f32_e32 v19, 0x3fb8aa3b, v19
	v_exp_f32_e32 v19, v19
	s_nop 0
	v_add_f32_e32 v19, 1.0, v19
	v_rcp_f32_e32 v20, v19
	v_mul_f32_e32 v19, 0x3d372713, v23
	v_mul_f32_e32 v19, v23, v19
	v_fma_f32 v19, v23, v19, v23
	v_mul_f32_e32 v19, 0x3f4c422a, v19
	v_add_f32_e32 v19, v19, v19
	v_mul_f32_e32 v19, 0x3fb8aa3b, v19
	v_exp_f32_e32 v19, v19
	v_pk_mul_f32 v[22:23], v[22:23], 0.5 op_sel_hi:[1,0]
	v_add_f32_e32 v19, 1.0, v19
	v_rcp_f32_e32 v21, v19
	s_nop 0
	v_pk_fma_f32 v[20:21], v[20:21], 2.0, 1.0 op_sel_hi:[1,0,0] neg_lo:[1,0,0] neg_hi:[1,0,0]
	s_nop 0
	v_pk_add_f32 v[20:21], v[20:21], 1.0 op_sel_hi:[1,0]
	s_nop 0
	v_pk_mul_f32 v[20:21], v[22:23], v[20:21]
	v_pk_mul_f32 v[22:23], v[30:31], 0.5 op_sel_hi:[1,0]
	v_cvt_pk_bf16_f32 v19, v20, v21
	ds_write2_b64 v32, v[16:17], v[18:19] offset1:2
	v_mul_f32_e32 v16, 0x3d372713, v24
	v_mul_f32_e32 v17, 0x3d372713, v25
	v_mul_f32_e32 v16, v24, v16
	v_mul_f32_e32 v17, v25, v17
	v_fma_f32 v16, v24, v16, v24
	v_fma_f32 v17, v25, v17, v25
	v_mul_f32_e32 v16, 0x3f4c422a, v16
	v_mul_f32_e32 v17, 0x3f4c422a, v17
	v_add_f32_e32 v16, v16, v16
	v_add_f32_e32 v17, v17, v17
	v_mul_f32_e32 v16, 0x3fb8aa3b, v16
	v_mul_f32_e32 v17, 0x3fb8aa3b, v17
	v_exp_f32_e32 v16, v16
	v_exp_f32_e32 v17, v17
	v_pk_mul_f32 v[18:19], v[24:25], 0.5 op_sel_hi:[1,0]
	v_pk_mul_f32 v[20:21], v[26:27], 0.5 op_sel_hi:[1,0]
	v_add_f32_e32 v16, 1.0, v16
	v_add_f32_e32 v17, 1.0, v17
	v_rcp_f32_e32 v16, v16
	v_rcp_f32_e32 v17, v17
	s_nop 0
	v_pk_fma_f32 v[16:17], v[16:17], 2.0, 1.0 op_sel_hi:[1,0,0] neg_lo:[1,0,0] neg_hi:[1,0,0]
	s_nop 0
	v_pk_add_f32 v[16:17], v[16:17], 1.0 op_sel_hi:[1,0]
	s_nop 0
	v_pk_mul_f32 v[16:17], v[18:19], v[16:17]
	s_nop 0
	v_cvt_pk_bf16_f32 v16, v16, v17
	v_mul_f32_e32 v17, 0x3d372713, v26
	v_mul_f32_e32 v17, v26, v17
	v_fma_f32 v17, v26, v17, v26
	v_mul_f32_e32 v17, 0x3f4c422a, v17
	v_add_f32_e32 v17, v17, v17
	v_mul_f32_e32 v17, 0x3fb8aa3b, v17
	v_exp_f32_e32 v17, v17
	s_nop 0
	v_add_f32_e32 v17, 1.0, v17
	v_rcp_f32_e32 v18, v17
	v_mul_f32_e32 v17, 0x3d372713, v27
	v_mul_f32_e32 v17, v27, v17
	v_fma_f32 v17, v27, v17, v27
	v_mul_f32_e32 v17, 0x3f4c422a, v17
	v_add_f32_e32 v17, v17, v17
	v_mul_f32_e32 v17, 0x3fb8aa3b, v17
	v_exp_f32_e32 v17, v17
	s_nop 0
	v_add_f32_e32 v17, 1.0, v17
	v_rcp_f32_e32 v19, v17
	s_nop 0
	v_pk_fma_f32 v[18:19], v[18:19], 2.0, 1.0 op_sel_hi:[1,0,0] neg_lo:[1,0,0] neg_hi:[1,0,0]
	s_nop 0
	v_pk_add_f32 v[18:19], v[18:19], 1.0 op_sel_hi:[1,0]
	s_nop 0
	v_pk_mul_f32 v[18:19], v[20:21], v[18:19]
	v_pk_mul_f32 v[20:21], v[28:29], 0.5 op_sel_hi:[1,0]
	v_cvt_pk_bf16_f32 v17, v18, v19
	v_mul_f32_e32 v18, 0x3d372713, v28
	v_mul_f32_e32 v19, 0x3d372713, v29
	v_mul_f32_e32 v18, v28, v18
	v_mul_f32_e32 v19, v29, v19
	v_fma_f32 v18, v28, v18, v28
	v_fma_f32 v19, v29, v19, v29
	v_mul_f32_e32 v18, 0x3f4c422a, v18
	v_mul_f32_e32 v19, 0x3f4c422a, v19
	v_add_f32_e32 v18, v18, v18
	v_add_f32_e32 v19, v19, v19
	v_mul_f32_e32 v18, 0x3fb8aa3b, v18
	v_mul_f32_e32 v19, 0x3fb8aa3b, v19
	v_exp_f32_e32 v18, v18
	v_exp_f32_e32 v19, v19
	v_add_f32_e32 v18, 1.0, v18
	v_add_f32_e32 v19, 1.0, v19
	v_rcp_f32_e32 v18, v18
	v_rcp_f32_e32 v19, v19
	s_nop 0
	v_pk_fma_f32 v[18:19], v[18:19], 2.0, 1.0 op_sel_hi:[1,0,0] neg_lo:[1,0,0] neg_hi:[1,0,0]
	s_nop 0
	v_pk_add_f32 v[18:19], v[18:19], 1.0 op_sel_hi:[1,0]
	s_nop 0
	v_pk_mul_f32 v[18:19], v[20:21], v[18:19]
	s_nop 0
	v_cvt_pk_bf16_f32 v18, v18, v19
	v_mul_f32_e32 v19, 0x3d372713, v30
	v_mul_f32_e32 v19, v30, v19
	v_fma_f32 v19, v30, v19, v30
	v_mul_f32_e32 v19, 0x3f4c422a, v19
	v_add_f32_e32 v19, v19, v19
	v_mul_f32_e32 v19, 0x3fb8aa3b, v19
; #define LAS __attribute__((address_space(3)))
; DI unsigned pk2(float lo, float hi) { const f32x2 v = {lo, hi}; return __builtin_bit_cast(unsigned, __builtin_convertvector(v, bf16v2)); }
; DI float frcp(float x) { return __builtin_amdgcn_rcpf(x); }
; DI float gelu_tanh(float x) {
;     const float t = 0.7978845608028654f * (x + 0.044715f * x * x * x);
;     const float e = __expf(2.f * t);
;     const float th = 1.f - 2.f * frcp(e + 1.f);
;     return 0.5f * x * (1.f + th);
; }
; DI void ssm_prompt_unit(LAS unsigned char* lds, int unit, int tid, int l, const bf16_t* U, const bf16_t* mats_l, const float* lam16_l, bf16_t* Z, float* outr_l, float* outi_l) {
;     ...
; #pragma unroll
;         for (int mt = 0; mt < 4; ++mt)
; #pragma unroll
;             for (int g4 = 0; g4 < 4; ++g4) {
;                 const int tok = 16 * (mt * 32 + l32) + 2 * wave + (g4 >> 1), c0 = 8 * (g4 & 1) + 4 * h;
;                 u32x2 w; w.x = pk2(gelu_tanh(acc[mt][4 * g4]), gelu_tanh(acc[mt][4 * g4 + 1])); w.y = pk2(gelu_tanh(acc[mt][4 * g4 + 2]), gelu_tanh(acc[mt][4 * g4 + 3]));
;                 *(LAS u32x2*)(lds + tok * 32 + c0 * 2) = w;
	v_exp_f32_e32 v19, v19
	s_nop 0
	v_add_f32_e32 v19, 1.0, v19
	v_rcp_f32_e32 v20, v19
	v_mul_f32_e32 v19, 0x3d372713, v31
	v_mul_f32_e32 v19, v31, v19
	v_fma_f32 v19, v31, v19, v31
	v_mul_f32_e32 v19, 0x3f4c422a, v19
	v_add_f32_e32 v19, v19, v19
	v_mul_f32_e32 v19, 0x3fb8aa3b, v19
	v_exp_f32_e32 v19, v19
	s_nop 0
	v_add_f32_e32 v19, 1.0, v19
	v_rcp_f32_e32 v21, v19
	s_nop 0
	v_pk_fma_f32 v[20:21], v[20:21], 2.0, 1.0 op_sel_hi:[1,0,0] neg_lo:[1,0,0] neg_hi:[1,0,0]
	s_nop 0
	v_pk_add_f32 v[20:21], v[20:21], 1.0 op_sel_hi:[1,0]
	s_nop 0
	v_pk_mul_f32 v[20:21], v[22:23], v[20:21]
	s_nop 0
	v_cvt_pk_bf16_f32 v19, v20, v21
	ds_write2_b64 v32, v[16:17], v[18:19] offset0:4 offset1:6
	v_mul_f32_e32 v16, 0x3d372713, v0
	v_mul_f32_e32 v17, 0x3d372713, v1
	v_mul_f32_e32 v16, v0, v16
	v_mul_f32_e32 v17, v1, v17
	v_fma_f32 v16, v0, v16, v0
	v_fma_f32 v17, v1, v17, v1
	v_mul_f32_e32 v16, 0x3f4c422a, v16
	v_mul_f32_e32 v17, 0x3f4c422a, v17
	v_add_f32_e32 v16, v16, v16
	v_add_f32_e32 v17, v17, v17
	v_mul_f32_e32 v16, 0x3fb8aa3b, v16
	v_mul_f32_e32 v17, 0x3fb8aa3b, v17
	v_exp_f32_e32 v16, v16
	v_exp_f32_e32 v17, v17
	v_pk_mul_f32 v[0:1], v[0:1], 0.5 op_sel_hi:[1,0]
	v_add_f32_e32 v16, 1.0, v16
	v_add_f32_e32 v17, 1.0, v17
	v_rcp_f32_e32 v16, v16
	v_rcp_f32_e32 v17, v17
	s_nop 0
	v_pk_fma_f32 v[16:17], v[16:17], 2.0, 1.0 op_sel_hi:[1,0,0] neg_lo:[1,0,0] neg_hi:[1,0,0]
	s_nop 0
	v_pk_add_f32 v[16:17], v[16:17], 1.0 op_sel_hi:[1,0]
	s_nop 0
	v_pk_mul_f32 v[0:1], v[0:1], v[16:17]
	s_nop 0
	v_cvt_pk_bf16_f32 v0, v0, v1
	v_mul_f32_e32 v1, 0x3d372713, v2
	v_mul_f32_e32 v1, v2, v1
	v_fma_f32 v1, v2, v1, v2
	v_mul_f32_e32 v1, 0x3f4c422a, v1
	v_add_f32_e32 v1, v1, v1
	v_mul_f32_e32 v1, 0x3fb8aa3b, v1
	v_exp_f32_e32 v1, v1
	s_nop 0
	v_add_f32_e32 v1, 1.0, v1
	v_rcp_f32_e32 v16, v1
	v_mul_f32_e32 v1, 0x3d372713, v3
	v_mul_f32_e32 v1, v3, v1
	v_fma_f32 v1, v3, v1, v3
	v_mul_f32_e32 v1, 0x3f4c422a, v1
	v_add_f32_e32 v1, v1, v1
	v_mul_f32_e32 v1, 0x3fb8aa3b, v1
	v_exp_f32_e32 v1, v1
	v_pk_mul_f32 v[2:3], v[2:3], 0.5 op_sel_hi:[1,0]
	v_add_f32_e32 v1, 1.0, v1
	v_rcp_f32_e32 v17, v1
	s_nop 0
	v_pk_fma_f32 v[16:17], v[16:17], 2.0, 1.0 op_sel_hi:[1,0,0] neg_lo:[1,0,0] neg_hi:[1,0,0]
	s_nop 0
	v_pk_add_f32 v[16:17], v[16:17], 1.0 op_sel_hi:[1,0]
	s_nop 0
	v_pk_mul_f32 v[2:3], v[2:3], v[16:17]
	v_add_u32_e32 v16, 0xc600, v198
	v_cvt_pk_bf16_f32 v1, v2, v3
	v_mul_f32_e32 v2, 0x3d372713, v4
	v_mul_f32_e32 v3, 0x3d372713, v5
	v_mul_f32_e32 v2, v4, v2
	v_mul_f32_e32 v3, v5, v3
	v_fma_f32 v2, v4, v2, v4
	v_fma_f32 v3, v5, v3, v5
	v_mul_f32_e32 v2, 0x3f4c422a, v2
	v_mul_f32_e32 v3, 0x3f4c422a, v3
	v_add_f32_e32 v2, v2, v2
	v_add_f32_e32 v3, v3, v3
	v_mul_f32_e32 v2, 0x3fb8aa3b, v2
	v_mul_f32_e32 v3, 0x3fb8aa3b, v3
	v_exp_f32_e32 v2, v2
	v_exp_f32_e32 v3, v3
	v_pk_mul_f32 v[4:5], v[4:5], 0.5 op_sel_hi:[1,0]
	v_add_f32_e32 v2, 1.0, v2
	v_add_f32_e32 v3, 1.0, v3
	v_rcp_f32_e32 v2, v2
	v_rcp_f32_e32 v3, v3
	s_nop 0
	v_pk_fma_f32 v[2:3], v[2:3], 2.0, 1.0 op_sel_hi:[1,0,0] neg_lo:[1,0,0] neg_hi:[1,0,0]
	s_nop 0
	v_pk_add_f32 v[2:3], v[2:3], 1.0 op_sel_hi:[1,0]
	s_nop 0
	v_pk_mul_f32 v[2:3], v[4:5], v[2:3]
	s_nop 0
	v_cvt_pk_bf16_f32 v2, v2, v3
	v_mul_f32_e32 v3, 0x3d372713, v6
	v_mul_f32_e32 v3, v6, v3
	v_fma_f32 v3, v6, v3, v6
	v_mul_f32_e32 v3, 0x3f4c422a, v3
	v_add_f32_e32 v3, v3, v3
	v_mul_f32_e32 v3, 0x3fb8aa3b, v3
	v_exp_f32_e32 v3, v3
	s_nop 0
	v_add_f32_e32 v3, 1.0, v3
	v_rcp_f32_e32 v4, v3
	v_mul_f32_e32 v3, 0x3d372713, v7
	v_mul_f32_e32 v3, v7, v3
	v_fma_f32 v3, v7, v3, v7
	v_mul_f32_e32 v3, 0x3f4c422a, v3
	v_add_f32_e32 v3, v3, v3
	v_mul_f32_e32 v3, 0x3fb8aa3b, v3
	v_exp_f32_e32 v3, v3
	v_pk_mul_f32 v[6:7], v[6:7], 0.5 op_sel_hi:[1,0]
	v_add_f32_e32 v3, 1.0, v3
	v_rcp_f32_e32 v5, v3
	s_nop 0
	v_pk_fma_f32 v[4:5], v[4:5], 2.0, 1.0 op_sel_hi:[1,0,0] neg_lo:[1,0,0] neg_hi:[1,0,0]
	s_nop 0
	v_pk_add_f32 v[4:5], v[4:5], 1.0 op_sel_hi:[1,0]
	s_nop 0
	v_pk_mul_f32 v[4:5], v[6:7], v[4:5]
	v_pk_mul_f32 v[6:7], v[14:15], 0.5 op_sel_hi:[1,0]
	v_cvt_pk_bf16_f32 v3, v4, v5
	ds_write2_b64 v16, v[0:1], v[2:3] offset1:2
; #define LAS __attribute__((address_space(3)))
; DI unsigned pk2(float lo, float hi) { const f32x2 v = {lo, hi}; return __builtin_bit_cast(unsigned, __builtin_convertvector(v, bf16v2)); }
; DI void ssm_prompt_unit(LAS unsigned char* lds, int unit, int tid, int l, const bf16_t* U, const bf16_t* mats_l, const float* lam16_l, bf16_t* Z, float* outr_l, float* outi_l) {
;     ...
; #pragma unroll
;         for (int mt = 0; mt < 4; ++mt)
; #pragma unroll
;             for (int g4 = 0; g4 < 4; ++g4) {
;                 const int tok = 16 * (mt * 32 + l32) + 2 * wave + (g4 >> 1), c0 = 8 * (g4 & 1) + 4 * h;
;                 u32x2 w; w.x = pk2(gelu_tanh(acc[mt][4 * g4]), gelu_tanh(acc[mt][4 * g4 + 1])); w.y = pk2(gelu_tanh(acc[mt][4 * g4 + 2]), gelu_tanh(acc[mt][4 * g4 + 3]));
;                 *(LAS u32x2*)(lds + tok * 32 + c0 * 2) = w;
;             }
;         __syncthreads();
;         for (int idx = tid; idx < 4096; idx += NTHREADS) {
;             const int t = idx >> 1, half = idx & 1;
;             *(u32x4*)(Z + (size_t)(b * SEQ + t) * SW + g * 16 + 8 * half) = *(const LAS u32x4*)(lds + t * 32 + half * 16);
	v_mul_f32_e32 v0, 0x3d372713, v8
	v_mul_f32_e32 v1, 0x3d372713, v9
	v_mul_f32_e32 v0, v8, v0
	v_mul_f32_e32 v1, v9, v1
	v_fma_f32 v0, v8, v0, v8
	v_fma_f32 v1, v9, v1, v9
	v_mul_f32_e32 v0, 0x3f4c422a, v0
	v_mul_f32_e32 v1, 0x3f4c422a, v1
	v_add_f32_e32 v0, v0, v0
	v_add_f32_e32 v1, v1, v1
	v_mul_f32_e32 v0, 0x3fb8aa3b, v0
	v_mul_f32_e32 v1, 0x3fb8aa3b, v1
	v_exp_f32_e32 v0, v0
	v_exp_f32_e32 v1, v1
	v_pk_mul_f32 v[2:3], v[8:9], 0.5 op_sel_hi:[1,0]
	v_pk_mul_f32 v[4:5], v[10:11], 0.5 op_sel_hi:[1,0]
	v_add_f32_e32 v0, 1.0, v0
	v_add_f32_e32 v1, 1.0, v1
	v_rcp_f32_e32 v0, v0
	v_rcp_f32_e32 v1, v1
	s_nop 0
	v_pk_fma_f32 v[0:1], v[0:1], 2.0, 1.0 op_sel_hi:[1,0,0] neg_lo:[1,0,0] neg_hi:[1,0,0]
	s_nop 0
	v_pk_add_f32 v[0:1], v[0:1], 1.0 op_sel_hi:[1,0]
	s_nop 0
	v_pk_mul_f32 v[0:1], v[2:3], v[0:1]
	s_nop 0
	v_cvt_pk_bf16_f32 v0, v0, v1
	v_mul_f32_e32 v1, 0x3d372713, v10
	v_mul_f32_e32 v1, v10, v1
	v_fma_f32 v1, v10, v1, v10
	v_mul_f32_e32 v1, 0x3f4c422a, v1
	v_add_f32_e32 v1, v1, v1
	v_mul_f32_e32 v1, 0x3fb8aa3b, v1
	v_exp_f32_e32 v1, v1
	s_nop 0
	v_add_f32_e32 v1, 1.0, v1
	v_rcp_f32_e32 v2, v1
	v_mul_f32_e32 v1, 0x3d372713, v11
	v_mul_f32_e32 v1, v11, v1
	v_fma_f32 v1, v11, v1, v11
	v_mul_f32_e32 v1, 0x3f4c422a, v1
	v_add_f32_e32 v1, v1, v1
	v_mul_f32_e32 v1, 0x3fb8aa3b, v1
	v_exp_f32_e32 v1, v1
	s_nop 0
	v_add_f32_e32 v1, 1.0, v1
	v_rcp_f32_e32 v3, v1
	s_nop 0
	v_pk_fma_f32 v[2:3], v[2:3], 2.0, 1.0 op_sel_hi:[1,0,0] neg_lo:[1,0,0] neg_hi:[1,0,0]
	s_nop 0
	v_pk_add_f32 v[2:3], v[2:3], 1.0 op_sel_hi:[1,0]
	s_nop 0
	v_pk_mul_f32 v[2:3], v[4:5], v[2:3]
	v_pk_mul_f32 v[4:5], v[12:13], 0.5 op_sel_hi:[1,0]
	v_cvt_pk_bf16_f32 v1, v2, v3
	v_mul_f32_e32 v2, 0x3d372713, v12
	v_mul_f32_e32 v3, 0x3d372713, v13
	v_mul_f32_e32 v2, v12, v2
	v_mul_f32_e32 v3, v13, v3
	v_fma_f32 v2, v12, v2, v12
	v_fma_f32 v3, v13, v3, v13
	v_mul_f32_e32 v2, 0x3f4c422a, v2
	v_mul_f32_e32 v3, 0x3f4c422a, v3
	v_add_f32_e32 v2, v2, v2
	v_add_f32_e32 v3, v3, v3
	v_mul_f32_e32 v2, 0x3fb8aa3b, v2
	v_mul_f32_e32 v3, 0x3fb8aa3b, v3
	v_exp_f32_e32 v2, v2
	v_exp_f32_e32 v3, v3
	v_add_f32_e32 v2, 1.0, v2
	v_add_f32_e32 v3, 1.0, v3
	v_rcp_f32_e32 v2, v2
	v_rcp_f32_e32 v3, v3
	s_nop 0
	v_pk_fma_f32 v[2:3], v[2:3], 2.0, 1.0 op_sel_hi:[1,0,0] neg_lo:[1,0,0] neg_hi:[1,0,0]
	s_nop 0
	v_pk_add_f32 v[2:3], v[2:3], 1.0 op_sel_hi:[1,0]
	s_nop 0
	v_pk_mul_f32 v[2:3], v[4:5], v[2:3]
	s_nop 0
	v_cvt_pk_bf16_f32 v2, v2, v3
	v_mul_f32_e32 v3, 0x3d372713, v14
	v_mul_f32_e32 v3, v14, v3
	v_fma_f32 v3, v14, v3, v14
	v_mul_f32_e32 v3, 0x3f4c422a, v3
	v_add_f32_e32 v3, v3, v3
	v_mul_f32_e32 v3, 0x3fb8aa3b, v3
	v_exp_f32_e32 v3, v3
	s_nop 0
	v_add_f32_e32 v3, 1.0, v3
	v_rcp_f32_e32 v4, v3
	v_mul_f32_e32 v3, 0x3d372713, v15
	v_mul_f32_e32 v3, v15, v3
	v_fma_f32 v3, v15, v3, v15
	v_mul_f32_e32 v3, 0x3f4c422a, v3
	v_add_f32_e32 v3, v3, v3
	v_mul_f32_e32 v3, 0x3fb8aa3b, v3
	v_exp_f32_e32 v3, v3
	s_nop 0
	v_add_f32_e32 v3, 1.0, v3
	v_rcp_f32_e32 v5, v3
	s_nop 0
	v_pk_fma_f32 v[4:5], v[4:5], 2.0, 1.0 op_sel_hi:[1,0,0] neg_lo:[1,0,0] neg_hi:[1,0,0]
	s_nop 0
	v_pk_add_f32 v[4:5], v[4:5], 1.0 op_sel_hi:[1,0]
	s_nop 0
	v_pk_mul_f32 v[4:5], v[6:7], v[4:5]
	s_nop 0
	v_cvt_pk_bf16_f32 v3, v4, v5
	ds_write2_b64 v16, v[0:1], v[2:3] offset0:4 offset1:6
	s_waitcnt lgkmcnt(0)
	s_barrier
	s_and_saveexec_b64 s[52:53], s[40:41]
	s_cbranch_execz .LBB0_398
	s_lshl_b32 s18, s14, 1
	v_lshl_add_u64 v[0:1], v[170:171], 0, s[18:19]
	s_mov_b64 s[54:55], 0
	v_mov_b32_e32 v2, v157
.LBB0_407:
	v_ashrrev_i32_e32 v3, 1, v2
	s_movk_i32 s6, 0xdff
	v_add_u32_e32 v9, 0x200, v2
	v_cmp_lt_i32_e32 vcc, s6, v2
	v_lshl_add_u32 v2, v3, 5, v183
	v_lshrrev_b32_e32 v199, 4, v3
	v_lshl_add_u32 v2, v199, 4, v2
	ds_read_b128 v[4:7], v2
	v_add_u32_e32 v8, s58, v3
	v_mov_b32_e32 v2, v9
	v_ashrrev_i32_e32 v9, 31, v8
	v_lshlrev_b64 v[8:9], 11, v[8:9]
	s_or_b64 s[54:55], vcc, s[54:55]
	v_lshl_add_u64 v[8:9], v[0:1], 0, v[8:9]
	s_waitcnt lgkmcnt(0)
	global_store_dwordx4 v[8:9], v[4:7], off
	s_andn2_b64 exec, exec, s[54:55]
	s_cbranch_execnz .LBB0_407
	s_branch .LBB0_398
